# prompt-attention inner loop hand-rescheduled: ks-major PV order, V fragments prefetched into free VGPRs, softmax VALU spread over MFMA gaps, DMA issue hidden in QK gaps
# speedup vs baseline: 1.0386x; 1.0074x over previous
; #define LAS __attribute__((address_space(3)))
; DI s16x4 vtr(const LAS char* p) { return __builtin_bit_cast(s16x4, __builtin_amdgcn_ds_read_tr16_b64_v4i16((LAS v4i16_t*)p)); }
; DI bf16x8 cat4(s16x4 lo, s16x4 hi) { return __builtin_shufflevector(lo, hi, 0, 1, 2, 3, 4, 5, 6, 7); }
; #define MFMA32(a, b, c) __builtin_amdgcn_mfma_f32_32x32x16_bf16((a), (b), (c), 0, 0, 0)
; DI void dma_tile(LAS char* slot, const bf16_t* Kg, const bf16_t* Vg, const unsigned (&poff)[5], int wid) {
; #pragma unroll
;     for (int j = 0; j < 5; ++j) { const int g0 = wid * 5 + j, gi = g0 > 36 ? 36 : g0;
;         { const bool isk = gi < 17; glds16(isk ? (const void*)Kg : (const void*)Vg, poff[j], (unsigned)(size_t)(isk ? slot + gi * 1024 : slot + SLOT_V + (gi - 17) * 1024)); } }
; }
; DI void attn_qk(const LAS char* kb, const bf16x8 (&qf)[4], bf16x8 (&pf)[4], float& l) {
;     f32x16 zero;
; #pragma unroll
;     for (int i = 0; i < 16; ++i) zero[i] = 0.f;
;     bf16x8 k0[4], k1[4];
; #pragma unroll
;     for (int s = 0; s < 4; ++s) k0[s] = *(const LAS bf16x8*)(kb + 32 * s);
; #pragma unroll
;     for (int s = 0; s < 4; ++s) k1[s] = *(const LAS bf16x8*)(kb + 32 * KRS + 32 * s);
;     f32x16 st0 = MFMA32(k0[0], qf[0], zero), st1 = MFMA32(k1[0], qf[0], zero);
; #pragma unroll
;     for (int s = 1; s < 4; ++s) { st0 = MFMA32(k0[s], qf[s], st0); st1 = MFMA32(k1[s], qf[s], st1); }
;     SGB(0x100, 8); SGB(0x008, 8);
;     float sum = 0.f;
; #pragma unroll
;     for (int i = 0; i < 16; ++i) { const float e = __builtin_amdgcn_exp2f(st0[i]); st0[i] = e; sum += e; }
;     pf[0] = pack8(st0, 0); pf[1] = pack8(st0, 1);
; #pragma unroll
;     for (int i = 0; i < 16; ++i) { const float e = __builtin_amdgcn_exp2f(st1[i]); st1[i] = e; sum += e; }
;     pf[2] = pack8(st1, 0); pf[3] = pack8(st1, 1);
;     l += sum;
; }
; DI void attn_pv(const LAS char* vb, const bf16x8 (&pf)[4], f32x16 (&O)[4]) {
;     s16x4 va[8], vc[8];
; #pragma unroll
;     for (int ks = 0; ks < 4; ++ks) { va[2 * ks] = vtr(vb + ks * 16 * VRS); va[2 * ks + 1] = vtr(vb + (ks * 16 + 8) * VRS); }
; #pragma unroll
;     for (int ks = 0; ks < 4; ++ks) { vc[2 * ks] = vtr(vb + ks * 16 * VRS + 64); vc[2 * ks + 1] = vtr(vb + (ks * 16 + 8) * VRS + 64); }
; #pragma unroll
;     for (int ks = 0; ks < 4; ++ks) O[0] = MFMA32(cat4(va[2 * ks], va[2 * ks + 1]), pf[ks], O[0]);
.LBB0_745:
	s_add_i32 s22, s21, 3
	s_min_i32 s24, s22, s6
	s_lshl_b32 s22, s24, 6
	s_add_i32 s22, s17, s22
	s_and_b32 s24, s24, 3
	s_ashr_i32 s23, s22, 31
	s_mul_i32 s24, s24, 0x9400
	s_lshl_b64 s[22:23], s[22:23], 10
	s_add_u32 s25, s16, s22
	s_addc_u32 s26, s18, s23
	s_add_u32 s27, s19, s22
	s_addc_u32 s34, s20, s23
	s_cmp_gt_i32 s21, s29
	s_cbranch_scc1 .Lattn_skip
	s_and_b32 s35, s21, 3
	s_mul_i32 s35, s35, 0x9400
	v_add_u32_e32 v0, s35, v174
	v_add_u32_e32 v14, s35, v134
	ds_read_b128 v[2:5], v0
	ds_read_b128 v[6:9], v0 offset:32
	ds_read_b128 v[10:13], v0 offset:64
	ds_read_b128 v[136:139], v0 offset:96
	ds_read_b128 v[140:143], v0 offset:8704
	ds_read_b128 v[144:147], v0 offset:8736
	ds_read_b128 v[148:151], v0 offset:8768
	ds_read_b128 v[196:199], v0 offset:8800
	s_and_b64 s[22:23], s[0:1], exec
	s_cselect_b32 s23, s26, s34
	s_cselect_b32 s22, s25, s27
	s_add_i32 s35, s24, s7
	s_mov_b32 m0, s35
	s_nop 0
	global_load_lds_dwordx4 v132, s[22:23]
	s_add_i32 s35, s24, s10
	s_addk_i32 s35, 0x400
	s_mov_b32 m0, s35
	s_nop 0
	global_load_lds_dwordx4 v131, s[22:23]
	s_and_b64 s[22:23], exec, s[8:9]
	s_cselect_b32 s23, s26, s34
	s_cselect_b32 s22, s25, s27
	s_waitcnt lgkmcnt(7)
	v_mfma_f32_32x32x16_bf16 v[96:111], v[2:5], v[112:115], 0
	ds_read_b64_tr_b16 v[200:201], v14 offset:17408
	ds_read_b64_tr_b16 v[202:203], v14 offset:19968
	s_waitcnt lgkmcnt(8)
	v_mfma_f32_32x32x16_bf16 v[96:111], v[6:9], v[116:119], v[96:111]
	ds_read_b64_tr_b16 v[204:205], v14 offset:17472
	ds_read_b64_tr_b16 v[206:207], v14 offset:20032
	s_add_i32 s35, s24, s11
	s_addk_i32 s35, 0x800
	s_mov_b32 m0, s35
	s_nop 0
	global_load_lds_dwordx4 v130, s[22:23]
	s_waitcnt lgkmcnt(9)
	v_mfma_f32_32x32x16_bf16 v[96:111], v[10:13], v[120:123], v[96:111]
	ds_read_b64_tr_b16 v[208:209], v14 offset:17536
	ds_read_b64_tr_b16 v[210:211], v14 offset:20096
	s_add_i32 s35, s24, s12
	s_addk_i32 s35, 0xc00
	s_mov_b32 m0, s35
	s_nop 0
	global_load_lds_dwordx4 v129, s[22:23]
	s_waitcnt lgkmcnt(10)
	v_mfma_f32_32x32x16_bf16 v[96:111], v[136:139], v[124:127], v[96:111]
	ds_read_b64_tr_b16 v[212:213], v14 offset:17600
	ds_read_b64_tr_b16 v[214:215], v14 offset:20160
	s_add_i32 s35, s24, s13
	s_addk_i32 s35, 0x1000
	s_mov_b32 m0, s35
	s_nop 0
	global_load_lds_dwordx4 v133, s[22:23]
	s_nop 0
	s_waitcnt lgkmcnt(11)
	v_mfma_f32_32x32x16_bf16 v[80:95], v[140:143], v[112:115], 0
	ds_read_b64_tr_b16 v[216:217], v14 offset:22528
	ds_read_b64_tr_b16 v[218:219], v14 offset:25088
	v_exp_f32_e32 v96, v96
	v_exp_f32_e32 v97, v97
	s_nop 0
	v_add_f32_e32 v15, v96, v97
	s_waitcnt lgkmcnt(12)
	v_mfma_f32_32x32x16_bf16 v[80:95], v[144:147], v[116:119], v[80:95]
	ds_read_b64_tr_b16 v[220:221], v14 offset:22592
	ds_read_b64_tr_b16 v[222:223], v14 offset:25152
	v_exp_f32_e32 v98, v98
	v_exp_f32_e32 v99, v99
	v_cvt_pk_bf16_f32 v96, v96, v97
	v_add_f32_e32 v15, v98, v15
	v_add_f32_e32 v15, v99, v15
	s_waitcnt lgkmcnt(13)
	v_mfma_f32_32x32x16_bf16 v[80:95], v[148:151], v[120:123], v[80:95]
	ds_read_b64_tr_b16 v[224:225], v14 offset:22656
	ds_read_b64_tr_b16 v[226:227], v14 offset:25216
	v_exp_f32_e32 v100, v100
	v_exp_f32_e32 v101, v101
	v_cvt_pk_bf16_f32 v97, v98, v99
	v_add_f32_e32 v15, v100, v15
	v_add_f32_e32 v15, v101, v15
	s_waitcnt lgkmcnt(14)
	v_mfma_f32_32x32x16_bf16 v[80:95], v[196:199], v[124:127], v[80:95]
	v_exp_f32_e32 v102, v102
	v_exp_f32_e32 v103, v103
	v_cvt_pk_bf16_f32 v98, v100, v101
	v_add_f32_e32 v15, v102, v15
	v_add_f32_e32 v15, v103, v15
	v_cvt_pk_bf16_f32 v99, v102, v103
	ds_read_b64_tr_b16 v[228:229], v14 offset:22720
	ds_read_b64_tr_b16 v[230:231], v14 offset:25280
	s_waitcnt lgkmcnt(14)
	v_mfma_f32_32x32x16_bf16 v[64:79], v[200:203], v[96:99], v[64:79]
	ds_read_b64_tr_b16 v[232:233], v14 offset:27648
	ds_read_b64_tr_b16 v[234:235], v14 offset:30208
	v_exp_f32_e32 v104, v104
	v_exp_f32_e32 v105, v105
	s_nop 0
	v_add_f32_e32 v15, v104, v15
	v_add_f32_e32 v15, v105, v15
	s_waitcnt lgkmcnt(14)
	v_mfma_f32_32x32x16_bf16 v[48:63], v[204:207], v[96:99], v[48:63]
	ds_read_b64_tr_b16 v[236:237], v14 offset:27712
	ds_read_b64_tr_b16 v[238:239], v14 offset:30272
	v_exp_f32_e32 v106, v106
	v_exp_f32_e32 v107, v107
	v_cvt_pk_bf16_f32 v104, v104, v105
	v_add_f32_e32 v15, v106, v15
	v_add_f32_e32 v15, v107, v15
	s_waitcnt lgkmcnt(14)
; #define LAS __attribute__((address_space(3)))
; DI s16x4 vtr(const LAS char* p) { return __builtin_bit_cast(s16x4, __builtin_amdgcn_ds_read_tr16_b64_v4i16((LAS v4i16_t*)p)); }
; DI void dma_tile(LAS char* slot, const bf16_t* Kg, const bf16_t* Vg, const unsigned (&poff)[5], int wid) {
; #pragma unroll
;     for (int j = 0; j < 5; ++j) { const int g0 = wid * 5 + j, gi = g0 > 36 ? 36 : g0;
;         { const bool isk = gi < 17; glds16(isk ? (const void*)Kg : (const void*)Vg, poff[j], (unsigned)(size_t)(isk ? slot + gi * 1024 : slot + SLOT_V + (gi - 17) * 1024)); } }
; DI void attn_qk(const LAS char* kb, const bf16x8 (&qf)[4], bf16x8 (&pf)[4], float& l) {
;     ...
;     for (int i = 0; i < 16; ++i) { const float e = __builtin_amdgcn_exp2f(st0[i]); st0[i] = e; sum += e; }
;     pf[0] = pack8(st0, 0); pf[1] = pack8(st0, 1);
; #pragma unroll
;     for (int i = 0; i < 16; ++i) { const float e = __builtin_amdgcn_exp2f(st1[i]); st1[i] = e; sum += e; }
;     pf[2] = pack8(st1, 0); pf[3] = pack8(st1, 1);
;     l += sum;
; }
; DI void attn_pv(const LAS char* vb, const bf16x8 (&pf)[4], f32x16 (&O)[4]) {
;     s16x4 va[8], vc[8];
; #pragma unroll
;     for (int ks = 0; ks < 4; ++ks) { va[2 * ks] = vtr(vb + ks * 16 * VRS); va[2 * ks + 1] = vtr(vb + (ks * 16 + 8) * VRS); }
; #pragma unroll
;     for (int ks = 0; ks < 4; ++ks) { vc[2 * ks] = vtr(vb + ks * 16 * VRS + 64); vc[2 * ks + 1] = vtr(vb + (ks * 16 + 8) * VRS + 64); }
; #pragma unroll
;     for (int ks = 0; ks < 4; ++ks) O[0] = MFMA32(cat4(va[2 * ks], va[2 * ks + 1]), pf[ks], O[0]);
; #pragma unroll
;     for (int ks = 0; ks < 4; ++ks) { va[2 * ks] = vtr(vb + ks * 16 * VRS + 128); va[2 * ks + 1] = vtr(vb + (ks * 16 + 8) * VRS + 128); }
;     SGB(0x100, 16); SGB(0x008, 4); SGB(0x100, 8);
; #pragma unroll
;     for (int ks = 0; ks < 4; ++ks) O[1] = MFMA32(cat4(vc[2 * ks], vc[2 * ks + 1]), pf[ks], O[1]);
; #pragma unroll
;     for (int ks = 0; ks < 4; ++ks) { vc[2 * ks] = vtr(vb + ks * 16 * VRS + 192); vc[2 * ks + 1] = vtr(vb + (ks * 16 + 8) * VRS + 192); }
;     SGB(0x008, 4); SGB(0x100, 8);
; #pragma unroll
;     for (int ks = 0; ks < 4; ++ks) O[2] = MFMA32(cat4(va[2 * ks], va[2 * ks + 1]), pf[ks], O[2]);
;     SGB(0x008, 4);
; #pragma unroll
;     for (int ks = 0; ks < 4; ++ks) O[3] = MFMA32(cat4(vc[2 * ks], vc[2 * ks + 1]), pf[ks], O[3]);
;     SGB(0x008, 4);
	v_mfma_f32_32x32x16_bf16 v[32:47], v[208:211], v[96:99], v[32:47]
	ds_read_b64_tr_b16 v[240:241], v14 offset:27776
	ds_read_b64_tr_b16 v[242:243], v14 offset:30336
	v_exp_f32_e32 v108, v108
	v_exp_f32_e32 v109, v109
	v_cvt_pk_bf16_f32 v105, v106, v107
	v_add_f32_e32 v15, v108, v15
	v_add_f32_e32 v15, v109, v15
	s_waitcnt lgkmcnt(14)
	v_mfma_f32_32x32x16_bf16 v[16:31], v[212:215], v[96:99], v[16:31]
	v_exp_f32_e32 v110, v110
	v_exp_f32_e32 v111, v111
	v_cvt_pk_bf16_f32 v106, v108, v109
	v_add_f32_e32 v15, v110, v15
	v_add_f32_e32 v15, v111, v15
	v_cvt_pk_bf16_f32 v107, v110, v111
	ds_read_b64_tr_b16 v[244:245], v14 offset:27840
	ds_read_b64_tr_b16 v[246:247], v14 offset:30400
	s_waitcnt lgkmcnt(14)
	v_mfma_f32_32x32x16_bf16 v[64:79], v[216:219], v[104:107], v[64:79]
	ds_read_b64_tr_b16 v[248:249], v14 offset:32768
	ds_read_b64_tr_b16 v[250:251], v14 offset:35328
	v_exp_f32_e32 v80, v80
	v_exp_f32_e32 v81, v81
	s_nop 0
	v_add_f32_e32 v15, v80, v15
	v_add_f32_e32 v15, v81, v15
	s_waitcnt lgkmcnt(14)
	v_mfma_f32_32x32x16_bf16 v[48:63], v[220:223], v[104:107], v[48:63]
	ds_read_b64_tr_b16 v[2:3], v14 offset:32832
	ds_read_b64_tr_b16 v[4:5], v14 offset:35392
	v_exp_f32_e32 v82, v82
	v_exp_f32_e32 v83, v83
	v_cvt_pk_bf16_f32 v80, v80, v81
	v_add_f32_e32 v15, v82, v15
	v_add_f32_e32 v15, v83, v15
	s_waitcnt lgkmcnt(14)
	v_mfma_f32_32x32x16_bf16 v[32:47], v[224:227], v[104:107], v[32:47]
	ds_read_b64_tr_b16 v[6:7], v14 offset:32896
	ds_read_b64_tr_b16 v[8:9], v14 offset:35456
	v_exp_f32_e32 v84, v84
	v_exp_f32_e32 v85, v85
	v_cvt_pk_bf16_f32 v81, v82, v83
	v_add_f32_e32 v15, v84, v15
	v_add_f32_e32 v15, v85, v15
	s_waitcnt lgkmcnt(14)
	v_mfma_f32_32x32x16_bf16 v[16:31], v[228:231], v[104:107], v[16:31]
	v_exp_f32_e32 v86, v86
	v_exp_f32_e32 v87, v87
	v_cvt_pk_bf16_f32 v82, v84, v85
	v_add_f32_e32 v15, v86, v15
	v_add_f32_e32 v15, v87, v15
	v_cvt_pk_bf16_f32 v83, v86, v87
	ds_read_b64_tr_b16 v[10:11], v14 offset:32960
	ds_read_b64_tr_b16 v[12:13], v14 offset:35520
	s_waitcnt lgkmcnt(14)
	v_mfma_f32_32x32x16_bf16 v[64:79], v[232:235], v[80:83], v[64:79]
	v_exp_f32_e32 v88, v88
	v_exp_f32_e32 v89, v89
	s_nop 0
	v_add_f32_e32 v15, v88, v15
	v_add_f32_e32 v15, v89, v15
	s_waitcnt lgkmcnt(12)
	v_mfma_f32_32x32x16_bf16 v[48:63], v[236:239], v[80:83], v[48:63]
	v_exp_f32_e32 v90, v90
	v_exp_f32_e32 v91, v91
	v_cvt_pk_bf16_f32 v88, v88, v89
	v_add_f32_e32 v15, v90, v15
	v_add_f32_e32 v15, v91, v15
	s_waitcnt lgkmcnt(10)
	v_mfma_f32_32x32x16_bf16 v[32:47], v[240:243], v[80:83], v[32:47]
	v_exp_f32_e32 v92, v92
	v_exp_f32_e32 v93, v93
	v_cvt_pk_bf16_f32 v89, v90, v91
	v_add_f32_e32 v15, v92, v15
	v_add_f32_e32 v15, v93, v15
	s_waitcnt lgkmcnt(8)
	v_mfma_f32_32x32x16_bf16 v[16:31], v[244:247], v[80:83], v[16:31]
	v_exp_f32_e32 v94, v94
	v_exp_f32_e32 v95, v95
	v_cvt_pk_bf16_f32 v90, v92, v93
	v_add_f32_e32 v15, v94, v15
	v_add_f32_e32 v15, v95, v15
	v_cvt_pk_bf16_f32 v91, v94, v95
	v_add_f32_e32 v175, v175, v15
	s_nop 0
	s_waitcnt lgkmcnt(6)
	v_mfma_f32_32x32x16_bf16 v[64:79], v[248:251], v[88:91], v[64:79]
	s_waitcnt lgkmcnt(4)
	v_mfma_f32_32x32x16_bf16 v[48:63], v[2:5], v[88:91], v[48:63]
	s_waitcnt lgkmcnt(2)
	v_mfma_f32_32x32x16_bf16 v[32:47], v[6:9], v[88:91], v[32:47]
	s_waitcnt lgkmcnt(0)
	v_mfma_f32_32x32x16_bf16 v[16:31], v[10:13], v[88:91], v[16:31]
	s_branch .LBB0_744
.Lattn_skip:
	s_and_b64 s[22:23], s[0:1], exec
	s_cselect_b32 s23, s26, s34
	s_cselect_b32 s22, s25, s27
	s_add_i32 s35, s24, s7
	s_mov_b32 m0, s35
	s_nop 0
	global_load_lds_dwordx4 v132, s[22:23]
	s_add_i32 s35, s24, s10
	s_addk_i32 s35, 0x400
	s_mov_b32 m0, s35
	s_nop 0
	global_load_lds_dwordx4 v131, s[22:23]
	s_and_b64 s[22:23], exec, s[8:9]
	s_cselect_b32 s23, s26, s34
	s_cselect_b32 s22, s25, s27
	s_add_i32 s35, s24, s11
	s_addk_i32 s35, 0x800
	s_mov_b32 m0, s35
	s_nop 0
	global_load_lds_dwordx4 v130, s[22:23]
	s_add_i32 s35, s24, s12
	s_addk_i32 s35, 0xc00
	s_mov_b32 m0, s35
	s_nop 0
	global_load_lds_dwordx4 v129, s[22:23]
	s_add_i32 s35, s24, s13
	s_addk_i32 s35, 0x1000
	s_mov_b32 m0, s35
	s_nop 0
	global_load_lds_dwordx4 v133, s[22:23]
	s_branch .LBB0_744
